# v27_stag120
# baseline (speedup 1.0000x reference)
; DI void dsa_item(const Params& p, int b, int blk) {
;     ...
;   #pragma unroll 1
;   for (int qq4x = 0; qq4x < 4 * REP_ATTN; ++qq4x) {
;     const int qq4 = qq4x & 3;
;     const int qq = w * 4 + qq4;
;     const int t = q0 + qq;
;     if (t >= LVALID) continue;
.Lsa_stag:
	s_cmp_eq_u32 s100, 0
	s_cbranch_scc1 .Lsa_stag_done
	s_sleep 120
	s_sub_u32 s100, s100, 1
	s_branch .Lsa_stag
